# attention softmax: pairs of v_sub_f32 (score - row max) on adjacent score registers -> one v_pk_add_f32 with a negated broadcast operand (69 of 80 pairs)
# speedup vs baseline: 1.0079x; 1.0028x over previous
.LBB0_347:
	v_cndmask_b32_e64 v72, v48, v212, s[2:3]
	v_cndmask_b32_e64 v167, v72, v48, s[4:5]
	v_max3_f32 v48, v98, s64, v105
	v_max3_f32 v48, v48, v104, v103
	v_max3_f32 v48, v48, v102, v101
	v_max3_f32 v48, v48, v100, v99
	v_max3_f32 v48, v48, v71, v70
	v_max3_f32 v48, v48, v69, v68
	v_max3_f32 v48, v48, v67, v66
	v_max3_f32 v48, v48, v65, v64
	v_max3_f32 v48, v48, v32, v33
	v_max3_f32 v48, v48, v34, v35
	v_max3_f32 v48, v48, v36, v37
	v_max3_f32 v48, v48, v38, v39
	v_max3_f32 v48, v48, v40, v41
	v_max3_f32 v48, v48, v42, v43
	v_max3_f32 v48, v48, v44, v45
	v_max3_f32 v48, v48, v46, v47
	v_max3_f32 v48, v48, v16, v17
	v_max3_f32 v48, v48, v18, v19
	v_max3_f32 v48, v48, v20, v21
	v_max3_f32 v48, v48, v22, v23
	v_max3_f32 v48, v48, v24, v25
	v_max3_f32 v48, v48, v26, v27
	v_max3_f32 v48, v48, v28, v29
	v_max3_f32 v48, v48, v30, v31
	v_max3_f32 v48, v48, v0, v1
	v_max3_f32 v48, v48, v2, v3
	v_max3_f32 v48, v48, v4, v5
	v_max3_f32 v48, v48, v6, v7
	v_max3_f32 v48, v48, v8, v9
	v_max3_f32 v48, v48, v10, v11
	v_max3_f32 v48, v48, v12, v13
	v_cndmask_b32_e64 v166, v212, v49, s[4:5]
	v_max3_f32 v48, v48, v14, v15
	v_cndmask_b32_e64 v168, v50, v212, s[6:7]
	v_cndmask_b32_e64 v169, v51, v212, s[8:9]
	v_max3_f32 v48, v48, v167, v166
	v_cndmask_b32_e64 v170, v52, v212, s[10:11]
	v_cndmask_b32_e64 v171, v53, v212, s[12:13]
	v_max3_f32 v48, v48, v168, v169
	v_cndmask_b32_e64 v172, v54, v212, s[14:15]
	v_cndmask_b32_e64 v173, v55, v212, s[16:17]
	v_max3_f32 v48, v48, v170, v171
	v_cndmask_b32_e64 v174, v56, v212, s[18:19]
	v_cndmask_b32_e64 v175, v57, v212, s[20:21]
	v_max3_f32 v48, v48, v172, v173
	v_cndmask_b32_e64 v176, v58, v212, s[22:23]
	v_cndmask_b32_e64 v177, v59, v212, s[24:25]
	v_max3_f32 v48, v48, v174, v175
	v_cndmask_b32_e64 v178, v60, v212, s[26:27]
	v_cndmask_b32_e64 v179, v61, v212, s[28:29]
	v_max3_f32 v48, v48, v176, v177
	v_cndmask_b32_e64 v180, v62, v212, s[30:31]
	v_cndmask_b32_e64 v181, v63, v212, s[34:35]
	v_max3_f32 v48, v48, v178, v179
	v_max3_f32 v48, v48, v180, v181
	ds_bpermute_b32 v49, v188, v48
	v_or_b32_e32 v153, s89, v118
	v_readlane_b32 s0, v255, 16
	s_add_i32 s96, s96, s1
	s_add_i32 s90, s90, s0
	s_waitcnt lgkmcnt(0)
	v_max3_f32 v213, v48, v49, v96
	v_sub_f32_e32 v50, v104, v213
	v_exp_f32_e32 v154, v50
	v_sub_f32_e32 v50, v103, v213
	v_exp_f32_e32 v155, v50
	v_sub_f32_e32 v50, v102, v213
	v_exp_f32_e32 v160, v50
	v_sub_f32_e32 v50, v101, v213
	v_exp_f32_e32 v161, v50
	v_sub_f32_e32 v50, v100, v213
	v_sub_f32_e32 v48, v98, v213
	v_exp_f32_e32 v164, v50
	v_sub_f32_e32 v50, v99, v213
	v_exp_f32_e32 v110, v48
	v_sub_f32_e32 v48, v105, v213
	v_exp_f32_e32 v165, v50
	v_sub_f32_e32 v50, v71, v213
	v_exp_f32_e32 v111, v48
	v_exp_f32_e32 v102, v50
	v_sub_f32_e32 v50, v70, v213
	v_exp_f32_e32 v103, v50
	v_pk_add_f32 v[232:233], v[68:69], v[212:213] op_sel:[0,1] op_sel_hi:[1,1] neg_lo:[0,1] neg_hi:[0,1]
	v_pk_add_f32 v[234:235], v[34:35], v[212:213] op_sel:[0,1] op_sel_hi:[1,1] neg_lo:[0,1] neg_hi:[0,1]
	v_exp_f32_e32 v112, v233
	v_exp_f32_e32 v106, v234
	v_exp_f32_e32 v113, v232
	v_pk_add_f32 v[232:233], v[66:67], v[212:213] op_sel:[0,1] op_sel_hi:[1,1] neg_lo:[0,1] neg_hi:[0,1]
	v_exp_f32_e32 v107, v235
	v_pk_add_f32 v[234:235], v[36:37], v[212:213] op_sel:[0,1] op_sel_hi:[1,1] neg_lo:[0,1] neg_hi:[0,1]
	v_pk_add_f32 v[48:49], v[110:111], 0 op_sel_hi:[1,0]
	v_exp_f32_e32 v156, v233
	v_exp_f32_e32 v118, v234
	v_pk_add_f32 v[48:49], v[154:155], v[48:49]
	v_exp_f32_e32 v157, v232
	v_pk_add_f32 v[232:233], v[64:65], v[212:213] op_sel:[0,1] op_sel_hi:[1,1] neg_lo:[0,1] neg_hi:[0,1]
	v_exp_f32_e32 v119, v235
	v_pk_add_f32 v[234:235], v[38:39], v[212:213] op_sel:[0,1] op_sel_hi:[1,1] neg_lo:[0,1] neg_hi:[0,1]
	v_pk_add_f32 v[48:49], v[160:161], v[48:49]
	v_exp_f32_e32 v162, v233
	v_pk_add_f32 v[236:237], v[32:33], v[212:213] op_sel:[0,1] op_sel_hi:[1,1] neg_lo:[0,1] neg_hi:[0,1]
	v_exp_f32_e32 v158, v234
	v_pk_add_f32 v[48:49], v[164:165], v[48:49]
	v_exp_f32_e32 v163, v232
	v_exp_f32_e32 v78, v236
	v_exp_f32_e32 v159, v235
	v_pk_add_f32 v[232:233], v[40:41], v[212:213] op_sel:[0,1] op_sel_hi:[1,1] neg_lo:[0,1] neg_hi:[0,1]
	v_pk_add_f32 v[48:49], v[102:103], v[48:49]
	v_exp_f32_e32 v79, v237
	v_exp_f32_e32 v68, v232
	v_pk_add_f32 v[48:49], v[112:113], v[48:49]
	v_exp_f32_e32 v69, v233
	v_pk_add_f32 v[232:233], v[42:43], v[212:213] op_sel:[0,1] op_sel_hi:[1,1] neg_lo:[0,1] neg_hi:[0,1]
	v_pk_add_f32 v[234:235], v[18:19], v[212:213] op_sel:[0,1] op_sel_hi:[1,1] neg_lo:[0,1] neg_hi:[0,1]
	v_pk_add_f32 v[236:237], v[2:3], v[212:213] op_sel:[0,1] op_sel_hi:[1,1] neg_lo:[0,1] neg_hi:[0,1]
	v_pk_add_f32 v[48:49], v[156:157], v[48:49]
	v_exp_f32_e32 v76, v232
	v_exp_f32_e32 v72, v234
	v_exp_f32_e32 v60, v236
	v_pk_add_f32 v[48:49], v[162:163], v[48:49]
	v_exp_f32_e32 v77, v233
	v_pk_add_f32 v[232:233], v[44:45], v[212:213] op_sel:[0,1] op_sel_hi:[1,1] neg_lo:[0,1] neg_hi:[0,1]
	v_exp_f32_e32 v73, v235
	v_pk_add_f32 v[234:235], v[20:21], v[212:213] op_sel:[0,1] op_sel_hi:[1,1] neg_lo:[0,1] neg_hi:[0,1]
	v_exp_f32_e32 v61, v237
	v_pk_add_f32 v[236:237], v[4:5], v[212:213] op_sel:[0,1] op_sel_hi:[1,1] neg_lo:[0,1] neg_hi:[0,1]
	v_pk_add_f32 v[32:33], v[78:79], v[48:49]
	v_exp_f32_e32 v104, v232
	v_exp_f32_e32 v100, v234
	v_exp_f32_e32 v66, v236
	v_pk_add_f32 v[32:33], v[106:107], v[32:33]
	v_exp_f32_e32 v105, v233
	v_pk_add_f32 v[232:233], v[46:47], v[212:213] op_sel:[0,1] op_sel_hi:[1,1] neg_lo:[0,1] neg_hi:[0,1]
	v_exp_f32_e32 v101, v235
	v_pk_add_f32 v[234:235], v[22:23], v[212:213] op_sel:[0,1] op_sel_hi:[1,1] neg_lo:[0,1] neg_hi:[0,1]
	v_exp_f32_e32 v67, v237
	v_pk_add_f32 v[236:237], v[6:7], v[212:213] op_sel:[0,1] op_sel_hi:[1,1] neg_lo:[0,1] neg_hi:[0,1]
	v_pk_add_f32 v[32:33], v[118:119], v[32:33]
	v_exp_f32_e32 v114, v232
	v_pk_add_f32 v[238:239], v[16:17], v[212:213] op_sel:[0,1] op_sel_hi:[1,1] neg_lo:[0,1] neg_hi:[0,1]
	v_exp_f32_e32 v108, v234
	v_exp_f32_e32 v74, v236
	v_pk_add_f32 v[32:33], v[158:159], v[32:33]
	v_exp_f32_e32 v115, v233
	v_exp_f32_e32 v64, v238
	v_exp_f32_e32 v109, v235
	v_pk_add_f32 v[232:233], v[24:25], v[212:213] op_sel:[0,1] op_sel_hi:[1,1] neg_lo:[0,1] neg_hi:[0,1]
	v_exp_f32_e32 v75, v237
	v_pk_add_f32 v[234:235], v[8:9], v[212:213] op_sel:[0,1] op_sel_hi:[1,1] neg_lo:[0,1] neg_hi:[0,1]
	v_pk_add_f32 v[32:33], v[68:69], v[32:33]
	v_exp_f32_e32 v65, v239
	v_exp_f32_e32 v58, v232
	v_exp_f32_e32 v48, v234
	v_pk_add_f32 v[32:33], v[76:77], v[32:33]
	v_exp_f32_e32 v59, v233
	v_pk_add_f32 v[232:233], v[26:27], v[212:213] op_sel:[0,1] op_sel_hi:[1,1] neg_lo:[0,1] neg_hi:[0,1]
	v_exp_f32_e32 v49, v235
	v_pk_add_f32 v[234:235], v[10:11], v[212:213] op_sel:[0,1] op_sel_hi:[1,1] neg_lo:[0,1] neg_hi:[0,1]
	v_pk_add_f32 v[32:33], v[104:105], v[32:33]
	v_exp_f32_e32 v62, v232
	v_exp_f32_e32 v50, v234
	v_pk_add_f32 v[32:33], v[114:115], v[32:33]
	v_exp_f32_e32 v63, v233
	v_pk_add_f32 v[232:233], v[28:29], v[212:213] op_sel:[0,1] op_sel_hi:[1,1] neg_lo:[0,1] neg_hi:[0,1]
	v_exp_f32_e32 v51, v235
	v_pk_add_f32 v[234:235], v[12:13], v[212:213] op_sel:[0,1] op_sel_hi:[1,1] neg_lo:[0,1] neg_hi:[0,1]
	v_pk_add_f32 v[16:17], v[64:65], v[32:33]
	v_exp_f32_e32 v70, v232
	v_exp_f32_e32 v52, v234
	v_pk_add_f32 v[16:17], v[72:73], v[16:17]
	v_exp_f32_e32 v71, v233
	v_pk_add_f32 v[232:233], v[30:31], v[212:213] op_sel:[0,1] op_sel_hi:[1,1] neg_lo:[0,1] neg_hi:[0,1]
	v_exp_f32_e32 v53, v235
	v_pk_add_f32 v[234:235], v[14:15], v[212:213] op_sel:[0,1] op_sel_hi:[1,1] neg_lo:[0,1] neg_hi:[0,1]
	v_pk_add_f32 v[16:17], v[100:101], v[16:17]
	v_exp_f32_e32 v98, v232
	v_pk_add_f32 v[236:237], v[0:1], v[212:213] op_sel:[0,1] op_sel_hi:[1,1] neg_lo:[0,1] neg_hi:[0,1]
	v_exp_f32_e32 v54, v234
	v_pk_add_f32 v[16:17], v[108:109], v[16:17]
	v_exp_f32_e32 v99, v233
	v_exp_f32_e32 v56, v236
	v_exp_f32_e32 v55, v235
	v_pk_add_f32 v[232:233], v[166:167], v[212:213] op_sel:[0,1] op_sel_hi:[1,1] neg_lo:[0,1] neg_hi:[0,1]
	v_pk_add_f32 v[16:17], v[58:59], v[16:17]
	v_exp_f32_e32 v57, v237
	v_exp_f32_e32 v40, v233
	v_pk_add_f32 v[16:17], v[62:63], v[16:17]
	v_exp_f32_e32 v41, v232
	v_pk_add_f32 v[232:233], v[168:169], v[212:213] op_sel:[0,1] op_sel_hi:[1,1] neg_lo:[0,1] neg_hi:[0,1]
	v_pk_add_f32 v[16:17], v[70:71], v[16:17]
	v_exp_f32_e32 v42, v232
	v_pk_add_f32 v[16:17], v[98:99], v[16:17]
	v_exp_f32_e32 v43, v233
	v_pk_add_f32 v[232:233], v[170:171], v[212:213] op_sel:[0,1] op_sel_hi:[1,1] neg_lo:[0,1] neg_hi:[0,1]
	v_pk_add_f32 v[0:1], v[56:57], v[16:17]
	v_exp_f32_e32 v44, v232
	v_pk_add_f32 v[0:1], v[60:61], v[0:1]
	v_exp_f32_e32 v45, v233
	v_pk_add_f32 v[232:233], v[172:173], v[212:213] op_sel:[0,1] op_sel_hi:[1,1] neg_lo:[0,1] neg_hi:[0,1]
	v_pk_add_f32 v[0:1], v[66:67], v[0:1]
	v_exp_f32_e32 v46, v232
	v_pk_add_f32 v[0:1], v[74:75], v[0:1]
	v_exp_f32_e32 v47, v233
	v_pk_add_f32 v[232:233], v[174:175], v[212:213] op_sel:[0,1] op_sel_hi:[1,1] neg_lo:[0,1] neg_hi:[0,1]
	v_pk_add_f32 v[0:1], v[48:49], v[0:1]
	v_exp_f32_e32 v32, v232
	v_pk_add_f32 v[0:1], v[50:51], v[0:1]
	v_exp_f32_e32 v33, v233
	v_pk_add_f32 v[232:233], v[176:177], v[212:213] op_sel:[0,1] op_sel_hi:[1,1] neg_lo:[0,1] neg_hi:[0,1]
	v_pk_add_f32 v[0:1], v[52:53], v[0:1]
	v_exp_f32_e32 v34, v232
	v_pk_add_f32 v[0:1], v[54:55], v[0:1]
	v_exp_f32_e32 v35, v233
	v_pk_add_f32 v[232:233], v[178:179], v[212:213] op_sel:[0,1] op_sel_hi:[1,1] neg_lo:[0,1] neg_hi:[0,1]
	v_pk_add_f32 v[0:1], v[40:41], v[0:1]
	v_exp_f32_e32 v36, v232
	v_pk_add_f32 v[0:1], v[42:43], v[0:1]
	v_exp_f32_e32 v37, v233
	v_pk_add_f32 v[232:233], v[180:181], v[212:213] op_sel:[0,1] op_sel_hi:[1,1] neg_lo:[0,1] neg_hi:[0,1]
	v_pk_add_f32 v[0:1], v[44:45], v[0:1]
	v_exp_f32_e32 v38, v232
	v_pk_add_f32 v[0:1], v[46:47], v[0:1]
	v_exp_f32_e32 v39, v233
	v_pk_add_f32 v[0:1], v[32:33], v[0:1]
	v_cvt_pk_bf16_f32 v16, v110, v111
	v_cvt_pk_bf16_f32 v17, v154, v155
	v_add_u32_e32 v154, 0x9000, v207
	v_pk_add_f32 v[0:1], v[34:35], v[0:1]
	v_cvt_pk_bf16_f32 v18, v160, v161
	v_cvt_pk_bf16_f32 v19, v164, v165
	v_add_u32_e32 v160, 0xd000, v207
	v_pk_add_f32 v[0:1], v[36:37], v[0:1]
	ds_read2_b64 v[20:23], v160 offset0:32 offset1:34
	v_pk_add_f32 v[0:1], v[38:39], v[0:1]
	s_nop 0
	v_add_f32_e32 v0, v0, v1
	ds_bpermute_b32 v1, v188, v0
	s_waitcnt lgkmcnt(0)
	v_add_f32_e32 v0, v0, v1
	v_sub_f32_e32 v1, v96, v213
	v_exp_f32_e32 v1, v1
	s_nop 0
	v_add_f32_e32 v96, v1, v0
	ds_read2_b64 v[0:3], v154 offset1:2
	v_cvt_pk_bf16_f32 v110, v102, v103
	v_cvt_pk_bf16_f32 v111, v112, v113
	v_cvt_pk_bf16_f32 v112, v156, v157
	v_cvt_pk_bf16_f32 v113, v162, v163
	ds_read2_b64 v[154:157], v154 offset0:4 offset1:6
	s_waitcnt lgkmcnt(1)
	v_mfma_f32_32x32x16_bf16 v[0:15], v[0:3], v[16:19], 0
	s_waitcnt lgkmcnt(0)
	v_mfma_f32_32x32x16_bf16 v[0:15], v[154:157], v[110:113], v[0:15]
	ds_read2_b64 v[154:157], v160 offset0:36 offset1:38
	v_mfma_f32_32x32x16_bf16 v[16:31], v[20:23], v[16:19], 0
	s_waitcnt lgkmcnt(0)
	v_mfma_f32_32x32x16_bf16 v[16:31], v[154:157], v[110:113], v[16:31]
	v_cvt_pk_bf16_f32 v110, v78, v79
	v_add_u32_e32 v78, 0x9000, v208
	v_cvt_pk_bf16_f32 v111, v106, v107
	v_cvt_pk_bf16_f32 v112, v118, v119
	v_cvt_pk_bf16_f32 v113, v158, v159
	ds_read2_b64 v[154:157], v78 offset1:2
	v_add_u32_e32 v106, 0xd000, v208
	s_waitcnt lgkmcnt(0)
	v_mfma_f32_32x32x16_bf16 v[0:15], v[154:157], v[110:113], v[0:15]
	ds_read2_b64 v[154:157], v106 offset0:32 offset1:34
	v_cvt_pk_bf16_f32 v102, v68, v69
	v_cvt_pk_bf16_f32 v103, v76, v77
	v_cvt_pk_bf16_f32 v104, v104, v105
	v_cvt_pk_bf16_f32 v105, v114, v115
	ds_read2_b64 v[76:79], v78 offset0:4 offset1:6
	s_waitcnt lgkmcnt(0)
	v_mfma_f32_32x32x16_bf16 v[0:15], v[76:79], v[102:105], v[0:15]
	ds_read2_b64 v[76:79], v106 offset0:36 offset1:38
	v_mfma_f32_32x32x16_bf16 v[16:31], v[154:157], v[110:113], v[16:31]
	s_waitcnt lgkmcnt(0)
	v_mfma_f32_32x32x16_bf16 v[16:31], v[76:79], v[102:105], v[16:31]
	v_cvt_pk_bf16_f32 v76, v64, v65
	v_add_u32_e32 v64, 0x9000, v209
	v_cvt_pk_bf16_f32 v77, v72, v73
	v_cvt_pk_bf16_f32 v78, v100, v101
	v_cvt_pk_bf16_f32 v79, v108, v109
	ds_read2_b64 v[100:103], v64 offset1:2
	v_add_u32_e32 v72, 0xd000, v209
	s_waitcnt lgkmcnt(0)
	v_mfma_f32_32x32x16_bf16 v[0:15], v[100:103], v[76:79], v[0:15]
	ds_read2_b64 v[100:103], v72 offset0:32 offset1:34
	v_cvt_pk_bf16_f32 v68, v58, v59
	v_cvt_pk_bf16_f32 v69, v62, v63
	v_cvt_pk_bf16_f32 v70, v70, v71
	v_cvt_pk_bf16_f32 v71, v98, v99
	ds_read2_b64 v[62:65], v64 offset0:4 offset1:6
	s_waitcnt lgkmcnt(0)
	v_mfma_f32_32x32x16_bf16 v[0:15], v[62:65], v[68:71], v[0:15]
	ds_read2_b64 v[62:65], v72 offset0:36 offset1:38
	v_cvt_pk_bf16_f32 v56, v56, v57
	v_cvt_pk_bf16_f32 v57, v60, v61
	v_cvt_pk_bf16_f32 v58, v66, v67
	v_cvt_pk_bf16_f32 v59, v74, v75
	v_mfma_f32_32x32x16_bf16 v[16:31], v[100:103], v[76:79], v[16:31]
	s_waitcnt lgkmcnt(0)
	v_mfma_f32_32x32x16_bf16 v[16:31], v[62:65], v[68:71], v[16:31]
	v_add_u32_e32 v64, 0x9000, v210
	ds_read2_b64 v[60:63], v64 offset1:2
	v_add_u32_e32 v65, 0xd000, v210
	s_waitcnt lgkmcnt(0)
	v_mfma_f32_32x32x16_bf16 v[0:15], v[60:63], v[56:59], v[0:15]
	ds_read2_b64 v[60:63], v65 offset0:32 offset1:34
	v_cvt_pk_bf16_f32 v48, v48, v49
	v_cvt_pk_bf16_f32 v49, v50, v51
	v_cvt_pk_bf16_f32 v50, v52, v53
	v_cvt_pk_bf16_f32 v51, v54, v55
	ds_read2_b64 v[52:55], v64 offset0:4 offset1:6
	s_waitcnt lgkmcnt(0)
	v_mfma_f32_32x32x16_bf16 v[0:15], v[52:55], v[48:51], v[0:15]
	ds_read2_b64 v[52:55], v65 offset0:36 offset1:38
	v_cvt_pk_bf16_f32 v40, v40, v41
	v_cvt_pk_bf16_f32 v41, v42, v43
	v_cvt_pk_bf16_f32 v42, v44, v45
	v_cvt_pk_bf16_f32 v43, v46, v47
	v_mfma_f32_32x32x16_bf16 v[16:31], v[60:63], v[56:59], v[16:31]
	s_waitcnt lgkmcnt(0)
	v_mfma_f32_32x32x16_bf16 v[16:31], v[52:55], v[48:51], v[16:31]
	v_add_u32_e32 v48, 0x9000, v211
	ds_read2_b64 v[44:47], v48 offset1:2
	v_add_u32_e32 v49, 0xd000, v211
	s_waitcnt lgkmcnt(0)
	v_mfma_f32_32x32x16_bf16 v[0:15], v[44:47], v[40:43], v[0:15]
	ds_read2_b64 v[44:47], v49 offset0:32 offset1:34
	v_cvt_pk_bf16_f32 v32, v32, v33
	v_cvt_pk_bf16_f32 v33, v34, v35
	v_cvt_pk_bf16_f32 v34, v36, v37
	v_cvt_pk_bf16_f32 v35, v38, v39
	ds_read2_b64 v[36:39], v48 offset0:4 offset1:6
	s_waitcnt lgkmcnt(0)
	v_mfma_f32_32x32x16_bf16 v[0:15], v[36:39], v[32:35], v[0:15]
	ds_read2_b64 v[36:39], v49 offset0:36 offset1:38
	v_mfma_f32_32x32x16_bf16 v[16:31], v[44:47], v[40:43], v[16:31]
	s_waitcnt lgkmcnt(0)
	v_mfma_f32_32x32x16_bf16 v[16:31], v[36:39], v[32:35], v[16:31]
	v_div_scale_f32 v32, s[68:69], v96, v96, 1.0
	v_rcp_f32_e32 v33, v32
	s_nop 0
	v_fma_f32 v34, -v32, v33, 1.0
	v_fmac_f32_e32 v33, v34, v33
	v_div_scale_f32 v34, vcc, 1.0, v96, 1.0
	v_mul_f32_e32 v35, v34, v33
	v_fma_f32 v36, -v32, v35, v34
	v_fmac_f32_e32 v35, v36, v33
	v_fma_f32 v32, -v32, v35, v34
	v_div_fmas_f32 v32, v32, v33, v35
	v_div_fixup_f32 v34, v32, v96, 1.0
	v_mul_f32_e32 v0, v0, v34
	v_mul_f32_e32 v1, v1, v34
	v_cvt_pk_bf16_f32 v0, v0, v1
	v_mul_f32_e32 v1, v2, v34
	v_mad_i64_i32 v[32:33], s[68:69], v153, s65, v[116:117]
	v_and_b32_e32 v36, 63, v251
	v_and_b32_e32 v35, 31, v251
	v_lshrrev_b32_e32 v37, 5, v36
	v_lshlrev_b32_e32 v37, 3, v37
	s_movk_i32 s58, 0x90
	v_mad_u32_u24 v35, v35, s58, v37
	s_movk_i32 s59, 0x1200
	v_mad_u32_u24 v35, v254, s59, v35
	v_add_u32_e32 v35, 0x12000, v35
	v_lshrrev_b32_e32 v37, 3, v36
	v_and_b32_e32 v40, 7, v36
	v_lshlrev_b32_e32 v40, 4, v40
	v_mad_u32_u24 v36, v37, s58, v40
	v_mad_u32_u24 v36, v254, s59, v36
	v_add_u32_e32 v36, 0x12000, v36
	s_movk_i32 s58, 0xc00
	v_mad_u32_u24 v37, v37, s58, v40
	v_readfirstlane_b32 s56, v32
	v_readfirstlane_b32 s57, v33
	v_mul_f32_e32 v2, v3, v34
	v_cvt_pk_bf16_f32 v1, v1, v2
	ds_write_b64 v35, v[0:1]
	v_mul_f32_e32 v0, v4, v34
	v_mul_f32_e32 v1, v5, v34
	v_cvt_pk_bf16_f32 v0, v0, v1
	v_mul_f32_e32 v1, v6, v34
	v_mul_f32_e32 v2, v7, v34
	v_cvt_pk_bf16_f32 v1, v1, v2
	ds_write_b64 v35, v[0:1] offset:16
	v_mul_f32_e32 v0, v8, v34
	v_mul_f32_e32 v1, v9, v34
	v_cvt_pk_bf16_f32 v0, v0, v1
	v_mul_f32_e32 v1, v10, v34
	v_mul_f32_e32 v2, v11, v34
	v_cvt_pk_bf16_f32 v1, v1, v2
	ds_write_b64 v35, v[0:1] offset:32
	v_mul_f32_e32 v0, v12, v34
	v_mul_f32_e32 v1, v13, v34
	v_cvt_pk_bf16_f32 v0, v0, v1
	v_mul_f32_e32 v1, v14, v34
	v_mul_f32_e32 v2, v15, v34
	v_cvt_pk_bf16_f32 v1, v1, v2
	ds_write_b64 v35, v[0:1] offset:48
	v_mul_f32_e32 v0, v16, v34
	v_mul_f32_e32 v1, v17, v34
	v_cvt_pk_bf16_f32 v0, v0, v1
	v_mul_f32_e32 v1, v18, v34
	v_mul_f32_e32 v2, v19, v34
	v_cvt_pk_bf16_f32 v1, v1, v2
	ds_write_b64 v35, v[0:1] offset:64
	v_mul_f32_e32 v0, v20, v34
	v_mul_f32_e32 v1, v21, v34
	v_cvt_pk_bf16_f32 v0, v0, v1
	v_mul_f32_e32 v1, v22, v34
	v_mul_f32_e32 v2, v23, v34
	v_cvt_pk_bf16_f32 v1, v1, v2
	ds_write_b64 v35, v[0:1] offset:80
	v_mul_f32_e32 v0, v24, v34
	v_mul_f32_e32 v1, v25, v34
	v_cvt_pk_bf16_f32 v0, v0, v1
	v_mul_f32_e32 v1, v26, v34
	v_mul_f32_e32 v2, v27, v34
	v_cvt_pk_bf16_f32 v1, v1, v2
	ds_write_b64 v35, v[0:1] offset:96
	v_mul_f32_e32 v0, v28, v34
	v_mul_f32_e32 v1, v29, v34
	v_cvt_pk_bf16_f32 v0, v0, v1
	v_mul_f32_e32 v1, v30, v34
	s_andn2_b64 vcc, exec, s[76:77]
	v_mul_f32_e32 v2, v31, v34
	v_cvt_pk_bf16_f32 v1, v1, v2
	ds_write_b64 v35, v[0:1] offset:112
	s_waitcnt lgkmcnt(0)
	ds_read_b128 v[0:3], v36
	ds_read_b128 v[4:7], v36 offset:1152
	ds_read_b128 v[8:11], v36 offset:2304
	ds_read_b128 v[12:15], v36 offset:3456
	s_waitcnt lgkmcnt(3)
	global_store_dwordx4 v37, v[0:3], s[56:57]
	s_add_u32 s56, s56, 0x6000
	s_addc_u32 s57, s57, 0
	s_waitcnt lgkmcnt(2)
	global_store_dwordx4 v37, v[4:7], s[56:57]
	s_add_u32 s56, s56, 0x6000
	s_addc_u32 s57, s57, 0
	s_waitcnt lgkmcnt(1)
	global_store_dwordx4 v37, v[8:11], s[56:57]
	s_add_u32 s56, s56, 0x6000
	s_addc_u32 s57, s57, 0
	s_waitcnt lgkmcnt(0)
	global_store_dwordx4 v37, v[12:15], s[56:57]
	s_nop 1
	s_setprio 0
	s_cbranch_vccz .Lattn_exit

.LBB0_357:
	s_mov_b32 s64, 0xff800000
	v_cndmask_b32_e64 v72, v48, v212, s[2:3]
	v_cndmask_b32_e64 v216, v72, v48, s[4:5]
	v_max3_f32 v48, v158, s64, v157
	v_max3_f32 v48, v48, v156, v155
	v_max3_f32 v48, v48, v154, v119
	v_max3_f32 v48, v48, v118, v99
	v_max3_f32 v48, v48, v71, v70
	v_max3_f32 v48, v48, v69, v68
	v_max3_f32 v48, v48, v67, v66
	v_max3_f32 v48, v48, v65, v64
	v_max3_f32 v48, v48, v32, v33
	v_max3_f32 v48, v48, v34, v35
	v_max3_f32 v48, v48, v36, v37
	v_max3_f32 v48, v48, v38, v39
	v_max3_f32 v48, v48, v40, v41
	v_max3_f32 v48, v48, v42, v43
	v_max3_f32 v48, v48, v44, v45
	v_max3_f32 v48, v48, v46, v47
	v_max3_f32 v48, v48, v16, v17
	v_max3_f32 v48, v48, v18, v19
	v_max3_f32 v48, v48, v20, v21
	v_max3_f32 v48, v48, v22, v23
	v_max3_f32 v48, v48, v24, v25
	v_max3_f32 v48, v48, v26, v27
	v_max3_f32 v48, v48, v28, v29
	v_max3_f32 v48, v48, v30, v31
	v_max3_f32 v48, v48, v0, v1
	v_max3_f32 v48, v48, v2, v3
	v_max3_f32 v48, v48, v4, v5
	v_max3_f32 v48, v48, v6, v7
	v_max3_f32 v48, v48, v8, v9
	v_max3_f32 v48, v48, v10, v11
	v_max3_f32 v48, v48, v12, v13
	v_cndmask_b32_e64 v215, v212, v49, s[4:5]
	v_max3_f32 v48, v48, v14, v15
	v_cndmask_b32_e64 v217, v50, v212, s[6:7]
	v_cndmask_b32_e64 v218, v51, v212, s[8:9]
	v_max3_f32 v48, v48, v216, v215
	v_cndmask_b32_e64 v219, v52, v212, s[10:11]
	v_cndmask_b32_e64 v220, v53, v212, s[12:13]
	v_max3_f32 v48, v48, v217, v218
	v_cndmask_b32_e64 v221, v54, v212, s[14:15]
	v_cndmask_b32_e64 v222, v55, v212, s[16:17]
	v_max3_f32 v48, v48, v219, v220
	v_cndmask_b32_e64 v223, v56, v212, s[18:19]
	v_cndmask_b32_e64 v224, v57, v212, s[20:21]
	v_max3_f32 v48, v48, v221, v222
	v_cndmask_b32_e64 v225, v58, v212, s[22:23]
	v_cndmask_b32_e64 v226, v59, v212, s[24:25]
	v_max3_f32 v48, v48, v223, v224
	v_cndmask_b32_e64 v227, v60, v212, s[26:27]
	v_cndmask_b32_e64 v228, v61, v212, s[28:29]
	v_max3_f32 v48, v48, v225, v226
	v_cndmask_b32_e64 v229, v62, v212, s[30:31]
	v_cndmask_b32_e64 v230, v63, v212, s[34:35]
	v_max3_f32 v48, v48, v227, v228
	v_max3_f32 v48, v48, v229, v230
	ds_bpermute_b32 v49, v188, v48
	v_mul_f32_e32 v96, 0x3fb8aa3b, v214
	v_or_b32_e32 v213, s89, v98
	s_mov_b32 s55, 0x3fb8aa3b
	s_lshl_b32 s94, s69, 1
	s_waitcnt lgkmcnt(0)
	v_max3_f32 v231, v48, v49, v96
	v_sub_f32_e32 v50, v156, v231
	v_exp_f32_e32 v170, v50
	v_sub_f32_e32 v50, v155, v231
	v_exp_f32_e32 v171, v50
	v_sub_f32_e32 v50, v154, v231
	v_exp_f32_e32 v176, v50
	v_sub_f32_e32 v50, v119, v231
	v_exp_f32_e32 v177, v50
	v_sub_f32_e32 v50, v118, v231
	v_sub_f32_e32 v48, v158, v231
	v_exp_f32_e32 v180, v50
	v_sub_f32_e32 v50, v99, v231
	v_exp_f32_e32 v162, v48
	v_sub_f32_e32 v48, v157, v231
	v_exp_f32_e32 v181, v50
	v_sub_f32_e32 v50, v71, v231
	v_exp_f32_e32 v163, v48
	v_exp_f32_e32 v154, v50
	v_sub_f32_e32 v50, v70, v231
	v_exp_f32_e32 v155, v50
	v_pk_add_f32 v[232:233], v[68:69], v[230:231] op_sel:[0,1] op_sel_hi:[1,1] neg_lo:[0,1] neg_hi:[0,1]
	v_pk_add_f32 v[234:235], v[34:35], v[230:231] op_sel:[0,1] op_sel_hi:[1,1] neg_lo:[0,1] neg_hi:[0,1]
	v_exp_f32_e32 v164, v233
	v_exp_f32_e32 v158, v234
	v_exp_f32_e32 v165, v232
	v_pk_add_f32 v[232:233], v[66:67], v[230:231] op_sel:[0,1] op_sel_hi:[1,1] neg_lo:[0,1] neg_hi:[0,1]
	v_exp_f32_e32 v159, v235
	v_pk_add_f32 v[234:235], v[36:37], v[230:231] op_sel:[0,1] op_sel_hi:[1,1] neg_lo:[0,1] neg_hi:[0,1]
	v_pk_add_f32 v[48:49], v[162:163], 0 op_sel_hi:[1,0]
	v_exp_f32_e32 v172, v233
	v_exp_f32_e32 v166, v234
	v_pk_add_f32 v[48:49], v[170:171], v[48:49]
	v_exp_f32_e32 v173, v232
	v_pk_add_f32 v[232:233], v[64:65], v[230:231] op_sel:[0,1] op_sel_hi:[1,1] neg_lo:[0,1] neg_hi:[0,1]
	v_exp_f32_e32 v167, v235
	v_pk_add_f32 v[234:235], v[38:39], v[230:231] op_sel:[0,1] op_sel_hi:[1,1] neg_lo:[0,1] neg_hi:[0,1]
	v_pk_add_f32 v[48:49], v[176:177], v[48:49]
	v_exp_f32_e32 v178, v233
	v_pk_add_f32 v[236:237], v[32:33], v[230:231] op_sel:[0,1] op_sel_hi:[1,1] neg_lo:[0,1] neg_hi:[0,1]
	v_exp_f32_e32 v174, v234
	v_pk_add_f32 v[48:49], v[180:181], v[48:49]
	v_exp_f32_e32 v179, v232
	v_exp_f32_e32 v78, v236
	v_exp_f32_e32 v175, v235
	v_pk_add_f32 v[232:233], v[40:41], v[230:231] op_sel:[0,1] op_sel_hi:[1,1] neg_lo:[0,1] neg_hi:[0,1]
	v_pk_add_f32 v[48:49], v[154:155], v[48:49]
	v_exp_f32_e32 v79, v237
	v_exp_f32_e32 v70, v232
	v_pk_add_f32 v[48:49], v[164:165], v[48:49]
	v_exp_f32_e32 v71, v233
	v_pk_add_f32 v[232:233], v[42:43], v[230:231] op_sel:[0,1] op_sel_hi:[1,1] neg_lo:[0,1] neg_hi:[0,1]
	v_pk_add_f32 v[234:235], v[18:19], v[230:231] op_sel:[0,1] op_sel_hi:[1,1] neg_lo:[0,1] neg_hi:[0,1]
	v_pk_add_f32 v[236:237], v[2:3], v[230:231] op_sel:[0,1] op_sel_hi:[1,1] neg_lo:[0,1] neg_hi:[0,1]
	v_pk_add_f32 v[48:49], v[172:173], v[48:49]
	v_exp_f32_e32 v76, v232
	v_exp_f32_e32 v74, v234
	v_exp_f32_e32 v60, v236
	v_pk_add_f32 v[48:49], v[178:179], v[48:49]
	v_exp_f32_e32 v77, v233
	v_pk_add_f32 v[232:233], v[44:45], v[230:231] op_sel:[0,1] op_sel_hi:[1,1] neg_lo:[0,1] neg_hi:[0,1]
	v_exp_f32_e32 v75, v235
	v_pk_add_f32 v[234:235], v[20:21], v[230:231] op_sel:[0,1] op_sel_hi:[1,1] neg_lo:[0,1] neg_hi:[0,1]
	v_exp_f32_e32 v61, v237
	v_pk_add_f32 v[236:237], v[4:5], v[230:231] op_sel:[0,1] op_sel_hi:[1,1] neg_lo:[0,1] neg_hi:[0,1]
	v_pk_add_f32 v[32:33], v[78:79], v[48:49]
	v_exp_f32_e32 v156, v232
	v_exp_f32_e32 v98, v234
	v_exp_f32_e32 v66, v236
	v_pk_add_f32 v[32:33], v[158:159], v[32:33]
	v_exp_f32_e32 v157, v233
	v_pk_add_f32 v[232:233], v[46:47], v[230:231] op_sel:[0,1] op_sel_hi:[1,1] neg_lo:[0,1] neg_hi:[0,1]
	v_exp_f32_e32 v99, v235
	v_pk_add_f32 v[234:235], v[22:23], v[230:231] op_sel:[0,1] op_sel_hi:[1,1] neg_lo:[0,1] neg_hi:[0,1]
	v_exp_f32_e32 v67, v237
	v_pk_add_f32 v[236:237], v[6:7], v[230:231] op_sel:[0,1] op_sel_hi:[1,1] neg_lo:[0,1] neg_hi:[0,1]
	v_pk_add_f32 v[32:33], v[166:167], v[32:33]
	v_exp_f32_e32 v168, v232
	v_pk_add_f32 v[238:239], v[16:17], v[230:231] op_sel:[0,1] op_sel_hi:[1,1] neg_lo:[0,1] neg_hi:[0,1]
	v_exp_f32_e32 v160, v234
	v_exp_f32_e32 v68, v236
	v_pk_add_f32 v[32:33], v[174:175], v[32:33]
	v_exp_f32_e32 v169, v233
	v_exp_f32_e32 v64, v238
	v_exp_f32_e32 v161, v235
	v_pk_add_f32 v[232:233], v[24:25], v[230:231] op_sel:[0,1] op_sel_hi:[1,1] neg_lo:[0,1] neg_hi:[0,1]
	v_exp_f32_e32 v69, v237
	v_pk_add_f32 v[234:235], v[8:9], v[230:231] op_sel:[0,1] op_sel_hi:[1,1] neg_lo:[0,1] neg_hi:[0,1]
	v_pk_add_f32 v[32:33], v[70:71], v[32:33]
	v_exp_f32_e32 v65, v239
	v_exp_f32_e32 v58, v232
	v_exp_f32_e32 v48, v234
	v_pk_add_f32 v[32:33], v[76:77], v[32:33]
	v_exp_f32_e32 v59, v233
	v_pk_add_f32 v[232:233], v[26:27], v[230:231] op_sel:[0,1] op_sel_hi:[1,1] neg_lo:[0,1] neg_hi:[0,1]
	v_exp_f32_e32 v49, v235
	v_pk_add_f32 v[234:235], v[10:11], v[230:231] op_sel:[0,1] op_sel_hi:[1,1] neg_lo:[0,1] neg_hi:[0,1]
	v_pk_add_f32 v[32:33], v[156:157], v[32:33]
	v_exp_f32_e32 v62, v232
	v_exp_f32_e32 v50, v234
	v_pk_add_f32 v[32:33], v[168:169], v[32:33]
	v_exp_f32_e32 v63, v233
	v_pk_add_f32 v[232:233], v[28:29], v[230:231] op_sel:[0,1] op_sel_hi:[1,1] neg_lo:[0,1] neg_hi:[0,1]
	v_exp_f32_e32 v51, v235
	v_pk_add_f32 v[234:235], v[12:13], v[230:231] op_sel:[0,1] op_sel_hi:[1,1] neg_lo:[0,1] neg_hi:[0,1]
	v_pk_add_f32 v[16:17], v[64:65], v[32:33]
	v_exp_f32_e32 v72, v232
	v_exp_f32_e32 v52, v234
	v_pk_add_f32 v[16:17], v[74:75], v[16:17]
	v_exp_f32_e32 v73, v233
	v_pk_add_f32 v[232:233], v[30:31], v[230:231] op_sel:[0,1] op_sel_hi:[1,1] neg_lo:[0,1] neg_hi:[0,1]
	v_exp_f32_e32 v53, v235
	v_pk_add_f32 v[234:235], v[14:15], v[230:231] op_sel:[0,1] op_sel_hi:[1,1] neg_lo:[0,1] neg_hi:[0,1]
	v_pk_add_f32 v[16:17], v[98:99], v[16:17]
	v_exp_f32_e32 v118, v232
	v_pk_add_f32 v[236:237], v[0:1], v[230:231] op_sel:[0,1] op_sel_hi:[1,1] neg_lo:[0,1] neg_hi:[0,1]
	v_exp_f32_e32 v54, v234
	v_pk_add_f32 v[16:17], v[160:161], v[16:17]
	v_exp_f32_e32 v119, v233
	v_exp_f32_e32 v56, v236
	v_exp_f32_e32 v55, v235
	v_pk_add_f32 v[232:233], v[216:217], v[230:231] op_sel:[0,1] op_sel_hi:[1,1] neg_lo:[0,1] neg_hi:[0,1]
	v_pk_add_f32 v[16:17], v[58:59], v[16:17]
	v_exp_f32_e32 v57, v237
	v_exp_f32_e32 v40, v232
	v_sub_f32_e32 v2, v215, v231
	v_pk_add_f32 v[16:17], v[62:63], v[16:17]
	v_exp_f32_e32 v41, v2
	v_pk_add_f32 v[16:17], v[72:73], v[16:17]
	v_exp_f32_e32 v42, v233
	v_pk_add_f32 v[232:233], v[218:219], v[230:231] op_sel:[0,1] op_sel_hi:[1,1] neg_lo:[0,1] neg_hi:[0,1]
	v_pk_add_f32 v[16:17], v[118:119], v[16:17]
	v_exp_f32_e32 v43, v232
	v_pk_add_f32 v[0:1], v[56:57], v[16:17]
	v_exp_f32_e32 v44, v233
	v_pk_add_f32 v[232:233], v[220:221], v[230:231] op_sel:[0,1] op_sel_hi:[1,1] neg_lo:[0,1] neg_hi:[0,1]
	v_pk_add_f32 v[0:1], v[60:61], v[0:1]
	v_exp_f32_e32 v45, v232
	v_pk_add_f32 v[0:1], v[66:67], v[0:1]
	v_exp_f32_e32 v46, v233
	v_pk_add_f32 v[232:233], v[222:223], v[230:231] op_sel:[0,1] op_sel_hi:[1,1] neg_lo:[0,1] neg_hi:[0,1]
	v_pk_add_f32 v[0:1], v[68:69], v[0:1]
	v_exp_f32_e32 v47, v232
	v_pk_add_f32 v[0:1], v[48:49], v[0:1]
	v_exp_f32_e32 v32, v233
	v_pk_add_f32 v[232:233], v[224:225], v[230:231] op_sel:[0,1] op_sel_hi:[1,1] neg_lo:[0,1] neg_hi:[0,1]
	v_pk_add_f32 v[0:1], v[50:51], v[0:1]
	v_exp_f32_e32 v33, v232
	v_pk_add_f32 v[0:1], v[52:53], v[0:1]
	v_exp_f32_e32 v34, v233
	v_pk_add_f32 v[232:233], v[226:227], v[230:231] op_sel:[0,1] op_sel_hi:[1,1] neg_lo:[0,1] neg_hi:[0,1]
	v_pk_add_f32 v[0:1], v[54:55], v[0:1]
	v_exp_f32_e32 v35, v232
	v_pk_add_f32 v[0:1], v[40:41], v[0:1]
	v_exp_f32_e32 v36, v233
	v_pk_add_f32 v[232:233], v[228:229], v[230:231] op_sel:[0,1] op_sel_hi:[1,1] neg_lo:[0,1] neg_hi:[0,1]
	v_pk_add_f32 v[0:1], v[42:43], v[0:1]
	v_exp_f32_e32 v37, v232
	v_pk_add_f32 v[0:1], v[44:45], v[0:1]
	v_exp_f32_e32 v38, v233
	v_sub_f32_e32 v2, v230, v231
	v_pk_add_f32 v[0:1], v[46:47], v[0:1]
	v_exp_f32_e32 v39, v2
	v_pk_add_f32 v[0:1], v[32:33], v[0:1]
	v_cvt_pk_bf16_f32 v16, v162, v163
	v_cvt_pk_bf16_f32 v17, v170, v171
	v_add_u32_e32 v170, 0x9000, v197
	v_pk_add_f32 v[0:1], v[34:35], v[0:1]
	v_cvt_pk_bf16_f32 v18, v176, v177
	v_cvt_pk_bf16_f32 v19, v180, v181
	v_add_u32_e32 v176, 0xd000, v197
	v_pk_add_f32 v[0:1], v[36:37], v[0:1]
	ds_read2_b64 v[20:23], v176 offset0:32 offset1:34
	v_pk_add_f32 v[0:1], v[38:39], v[0:1]
	v_lshl_add_u64 v[116:117], v[146:147], 0, s[94:95]
	v_add_f32_e32 v0, v0, v1
	ds_bpermute_b32 v1, v188, v0
	s_mov_b32 s97, s0
	v_readlane_b32 s0, v255, 15
	s_waitcnt lgkmcnt(0)
	v_add_f32_e32 v0, v0, v1
	v_fma_f32 v1, v214, s55, -v231
	v_exp_f32_e32 v1, v1
	s_nop 0
	v_add_f32_e32 v214, v1, v0
	ds_read2_b64 v[0:3], v170 offset1:2
	v_cvt_pk_bf16_f32 v162, v154, v155
	v_cvt_pk_bf16_f32 v163, v164, v165
	v_cvt_pk_bf16_f32 v164, v172, v173
	v_cvt_pk_bf16_f32 v165, v178, v179
	ds_read2_b64 v[170:173], v170 offset0:4 offset1:6
	s_waitcnt lgkmcnt(1)
	v_mfma_f32_32x32x16_bf16 v[0:15], v[0:3], v[16:19], 0
	s_waitcnt lgkmcnt(0)
	v_mfma_f32_32x32x16_bf16 v[0:15], v[170:173], v[162:165], v[0:15]
	ds_read2_b64 v[170:173], v176 offset0:36 offset1:38
	v_mfma_f32_32x32x16_bf16 v[16:31], v[20:23], v[16:19], 0
	s_waitcnt lgkmcnt(0)
	v_mfma_f32_32x32x16_bf16 v[16:31], v[170:173], v[162:165], v[16:31]
	v_cvt_pk_bf16_f32 v162, v78, v79
	v_add_u32_e32 v78, 0x9000, v198
	v_cvt_pk_bf16_f32 v163, v158, v159
	v_cvt_pk_bf16_f32 v164, v166, v167
	v_cvt_pk_bf16_f32 v165, v174, v175
	ds_read2_b64 v[170:173], v78 offset1:2
	v_add_u32_e32 v158, 0xd000, v198
	s_waitcnt lgkmcnt(0)
	v_mfma_f32_32x32x16_bf16 v[0:15], v[170:173], v[162:165], v[0:15]
	ds_read2_b64 v[170:173], v158 offset0:32 offset1:34
	v_cvt_pk_bf16_f32 v154, v70, v71
	v_cvt_pk_bf16_f32 v155, v76, v77
	v_cvt_pk_bf16_f32 v156, v156, v157
	v_cvt_pk_bf16_f32 v157, v168, v169
	ds_read2_b64 v[76:79], v78 offset0:4 offset1:6
	s_waitcnt lgkmcnt(0)
	v_mfma_f32_32x32x16_bf16 v[0:15], v[76:79], v[154:157], v[0:15]
	ds_read2_b64 v[76:79], v158 offset0:36 offset1:38
	v_mfma_f32_32x32x16_bf16 v[16:31], v[170:173], v[162:165], v[16:31]
	s_waitcnt lgkmcnt(0)
	v_mfma_f32_32x32x16_bf16 v[16:31], v[76:79], v[154:157], v[16:31]
	v_cvt_pk_bf16_f32 v76, v64, v65
	v_add_u32_e32 v64, 0x9000, v199
	v_cvt_pk_bf16_f32 v77, v74, v75
	v_cvt_pk_bf16_f32 v78, v98, v99
	v_cvt_pk_bf16_f32 v79, v160, v161
	ds_read2_b64 v[154:157], v64 offset1:2
	v_add_u32_e32 v74, 0xd000, v199
	s_waitcnt lgkmcnt(0)
	v_mfma_f32_32x32x16_bf16 v[0:15], v[154:157], v[76:79], v[0:15]
	ds_read2_b64 v[154:157], v74 offset0:32 offset1:34
	v_cvt_pk_bf16_f32 v70, v58, v59
	v_cvt_pk_bf16_f32 v71, v62, v63
	v_cvt_pk_bf16_f32 v72, v72, v73
	v_cvt_pk_bf16_f32 v73, v118, v119
	ds_read2_b64 v[62:65], v64 offset0:4 offset1:6
	v_or_b32_e32 v118, s0, v153
	s_waitcnt lgkmcnt(0)
	v_mfma_f32_32x32x16_bf16 v[0:15], v[62:65], v[70:73], v[0:15]
	ds_read2_b64 v[62:65], v74 offset0:36 offset1:38
	v_cvt_pk_bf16_f32 v56, v56, v57
	v_cvt_pk_bf16_f32 v57, v60, v61
	v_cvt_pk_bf16_f32 v58, v66, v67
	v_cvt_pk_bf16_f32 v59, v68, v69
	v_and_b32_e32 v67, 0xffff0000, v103
	v_and_b32_e32 v66, 0xffff0000, v107
	v_mfma_f32_32x32x16_bf16 v[16:31], v[154:157], v[76:79], v[16:31]
	v_lshlrev_b32_e32 v155, 16, v100
	v_lshlrev_b32_e32 v154, 16, v104
	v_and_b32_e32 v79, 0xffff0000, v102
	v_mul_f32_e64 v156, v154, v154
	v_mul_f32_e64 v157, v155, v155
	v_and_b32_e32 v78, 0xffff0000, v106
	v_pk_mul_f32 v[98:99], v[78:79], v[78:79]
	v_pk_mul_f32 v[68:69], v[66:67], v[66:67]
	s_waitcnt lgkmcnt(0)
	v_mfma_f32_32x32x16_bf16 v[16:31], v[62:65], v[70:73], v[16:31]
	v_add_u32_e32 v64, 0x9000, v200
	ds_read2_b64 v[60:63], v64 offset1:2
	v_add_u32_e32 v65, 0xd000, v200
	v_lshlrev_b32_e32 v71, 16, v102
	v_lshlrev_b32_e32 v102, 16, v105
	v_lshlrev_b32_e32 v70, 16, v106
	v_pk_mul_f32 v[72:73], v[70:71], v[70:71]
	s_waitcnt lgkmcnt(0)
	v_mfma_f32_32x32x16_bf16 v[0:15], v[60:63], v[56:59], v[0:15]
	ds_read2_b64 v[60:63], v65 offset0:32 offset1:34
	v_cvt_pk_bf16_f32 v48, v48, v49
	v_cvt_pk_bf16_f32 v49, v50, v51
	v_cvt_pk_bf16_f32 v50, v52, v53
	v_cvt_pk_bf16_f32 v51, v54, v55
	ds_read2_b64 v[52:55], v64 offset0:4 offset1:6
	s_waitcnt lgkmcnt(0)
	v_mfma_f32_32x32x16_bf16 v[0:15], v[52:55], v[48:51], v[0:15]
	ds_read2_b64 v[52:55], v65 offset0:36 offset1:38
	v_cvt_pk_bf16_f32 v40, v40, v41
	v_cvt_pk_bf16_f32 v41, v42, v43
	v_cvt_pk_bf16_f32 v42, v44, v45
	v_cvt_pk_bf16_f32 v43, v46, v47
	v_mfma_f32_32x32x16_bf16 v[16:31], v[60:63], v[56:59], v[16:31]
	v_lshlrev_b32_e32 v59, 16, v103
	v_lshlrev_b32_e32 v103, 16, v101
	v_lshlrev_b32_e32 v58, 16, v107
	v_mul_f32_e64 v106, v102, v102
	v_mul_f32_e64 v107, v103, v103
	v_pk_mul_f32 v[60:61], v[58:59], v[58:59]
	s_waitcnt lgkmcnt(0)
	v_mfma_f32_32x32x16_bf16 v[16:31], v[52:55], v[48:51], v[16:31]
	v_add_u32_e32 v48, 0x9000, v201
	ds_read2_b64 v[44:47], v48 offset1:2
	v_add_u32_e32 v49, 0xd000, v201
	s_waitcnt lgkmcnt(0)
	v_mfma_f32_32x32x16_bf16 v[0:15], v[44:47], v[40:43], v[0:15]
	ds_read2_b64 v[44:47], v49 offset0:32 offset1:34
	v_cvt_pk_bf16_f32 v32, v32, v33
	v_cvt_pk_bf16_f32 v33, v34, v35
	v_cvt_pk_bf16_f32 v34, v36, v37
	v_cvt_pk_bf16_f32 v35, v38, v39
	ds_read2_b64 v[36:39], v48 offset0:4 offset1:6
	s_waitcnt lgkmcnt(0)
	v_mfma_f32_32x32x16_bf16 v[0:15], v[36:39], v[32:35], v[0:15]
	ds_read2_b64 v[36:39], v49 offset0:36 offset1:38
	v_mfma_f32_32x32x16_bf16 v[16:31], v[44:47], v[40:43], v[16:31]
	v_lshlrev_b32_e32 v42, 16, v112
	v_lshlrev_b32_e32 v43, 16, v108
	v_mul_f32_e64 v54, v42, v42
	v_mul_f32_e64 v55, v43, v43
	s_waitcnt lgkmcnt(0)
	v_mfma_f32_32x32x16_bf16 v[16:31], v[36:39], v[32:35], v[16:31]
	v_div_scale_f32 v32, s[68:69], v214, v214, 1.0
	v_rcp_f32_e32 v33, v32
	v_lshlrev_b32_e32 v38, 16, v113
	v_mov_b32_e32 v41, v38
	v_lshlrev_b32_e32 v39, 16, v109
	v_fma_f32 v34, -v32, v33, 1.0
	v_fmac_f32_e32 v33, v34, v33
	v_div_scale_f32 v34, vcc, 1.0, v214, 1.0
	v_mul_f32_e32 v35, v34, v33
	v_fma_f32 v36, -v32, v35, v34
	v_fmac_f32_e32 v35, v36, v33
	v_fma_f32 v32, -v32, v35, v34
	v_div_fmas_f32 v32, v32, v33, v35
	v_div_fixup_f32 v34, v32, v214, 1.0
	v_mul_f32_e32 v0, v0, v34
	v_mul_f32_e32 v1, v1, v34
	v_cvt_pk_bf16_f32 v0, v0, v1
	v_mul_f32_e32 v1, v2, v34
	v_mad_i64_i32 v[32:33], s[68:69], v213, s65, v[116:117]
	v_and_b32_e32 v36, 63, v251
	v_and_b32_e32 v35, 31, v251
	v_lshrrev_b32_e32 v37, 5, v36
	v_lshlrev_b32_e32 v37, 3, v37
	s_movk_i32 s58, 0x90
	v_mad_u32_u24 v35, v35, s58, v37
	s_movk_i32 s59, 0x1200
	v_mad_u32_u24 v35, v254, s59, v35
	v_add_u32_e32 v35, 0x12000, v35
	v_lshrrev_b32_e32 v37, 3, v36
	v_and_b32_e32 v40, 7, v36
	v_lshlrev_b32_e32 v40, 4, v40
	v_mad_u32_u24 v36, v37, s58, v40
	v_mad_u32_u24 v36, v254, s59, v36
	v_add_u32_e32 v36, 0x12000, v36
	s_movk_i32 s58, 0xc00
	v_mad_u32_u24 v37, v37, s58, v40
	v_readfirstlane_b32 s56, v32
	v_readfirstlane_b32 s57, v33
	v_mul_f32_e32 v2, v3, v34
	v_cvt_pk_bf16_f32 v1, v1, v2
	ds_write_b64 v35, v[0:1]
	v_mul_f32_e32 v0, v4, v34
	v_mul_f32_e32 v1, v5, v34
	v_cvt_pk_bf16_f32 v0, v0, v1
	v_mul_f32_e32 v1, v6, v34
	v_mul_f32_e32 v2, v7, v34
	v_cvt_pk_bf16_f32 v1, v1, v2
	ds_write_b64 v35, v[0:1] offset:16
	v_mul_f32_e32 v0, v8, v34
	v_mul_f32_e32 v1, v9, v34
	v_cvt_pk_bf16_f32 v0, v0, v1
	v_mul_f32_e32 v1, v10, v34
	v_mul_f32_e32 v2, v11, v34
	v_cvt_pk_bf16_f32 v1, v1, v2
	ds_write_b64 v35, v[0:1] offset:32
	v_mul_f32_e32 v0, v12, v34
	v_mul_f32_e32 v1, v13, v34
	v_cvt_pk_bf16_f32 v0, v0, v1
	v_mul_f32_e32 v1, v14, v34
	v_mul_f32_e32 v2, v15, v34
	v_cvt_pk_bf16_f32 v1, v1, v2
	ds_write_b64 v35, v[0:1] offset:48
	v_mul_f32_e32 v0, v16, v34
	v_mul_f32_e32 v1, v17, v34
	v_cvt_pk_bf16_f32 v0, v0, v1
	v_mul_f32_e32 v1, v18, v34
	v_mul_f32_e32 v2, v19, v34
	v_cvt_pk_bf16_f32 v1, v1, v2
	ds_write_b64 v35, v[0:1] offset:64
	v_mul_f32_e32 v0, v20, v34
	v_mul_f32_e32 v1, v21, v34
	v_cvt_pk_bf16_f32 v0, v0, v1
	v_mul_f32_e32 v1, v22, v34
	v_mul_f32_e32 v2, v23, v34
	v_cvt_pk_bf16_f32 v1, v1, v2
	ds_write_b64 v35, v[0:1] offset:80
	v_mul_f32_e32 v0, v24, v34
	v_mul_f32_e32 v1, v25, v34
	v_cvt_pk_bf16_f32 v0, v0, v1
	v_mul_f32_e32 v1, v26, v34
	v_mul_f32_e32 v2, v27, v34
	v_cvt_pk_bf16_f32 v1, v1, v2
	ds_write_b64 v35, v[0:1] offset:96
	v_mul_f32_e32 v0, v28, v34
	v_mul_f32_e32 v1, v29, v34
	v_cvt_pk_bf16_f32 v0, v0, v1
	v_mul_f32_e32 v1, v30, v34
	v_mul_f32_e32 v2, v31, v34
	v_cvt_pk_bf16_f32 v1, v1, v2
	ds_write_b64 v35, v[0:1] offset:112
	s_waitcnt lgkmcnt(0)
	ds_read_b128 v[0:3], v36
	ds_read_b128 v[4:7], v36 offset:1152
	ds_read_b128 v[8:11], v36 offset:2304
	ds_read_b128 v[12:15], v36 offset:3456
	s_waitcnt lgkmcnt(3)
	global_store_dwordx4 v37, v[0:3], s[56:57]
	s_add_u32 s56, s56, 0x6000
	s_addc_u32 s57, s57, 0
	s_waitcnt lgkmcnt(2)
	global_store_dwordx4 v37, v[4:7], s[56:57]
	s_add_u32 s56, s56, 0x6000
	s_addc_u32 s57, s57, 0
	s_waitcnt lgkmcnt(1)
	global_store_dwordx4 v37, v[8:11], s[56:57]
	s_add_u32 s56, s56, 0x6000
	s_addc_u32 s57, s57, 0
	s_waitcnt lgkmcnt(0)
	global_store_dwordx4 v37, v[12:15], s[56:57]
	s_nop 1
	s_and_b64 vcc, exec, s[76:77]
	s_cbranch_vccnz .Lvpf_skip
	s_lshl_b32 s58, s33, 5
	s_and_b32 s58, s58, 0x780
	s_addk_i32 s58, 0xff80
	v_add_u32_e32 v16, s58, v183
	v_cmp_lt_i32_e32 vcc, -1, v16
	v_mov_b32_e32 v122, 0
	v_mov_b32_e32 v123, 0
	v_mov_b32_e32 v124, 0
	v_mov_b32_e32 v125, 0
	v_mov_b32_e32 v128, 0
	v_mov_b32_e32 v129, 0
	v_mov_b32_e32 v130, 0
	v_mov_b32_e32 v131, 0
	v_mov_b32_e32 v132, 0
	v_mov_b32_e32 v133, 0
	v_mov_b32_e32 v134, 0
	v_mov_b32_e32 v135, 0
	v_mov_b32_e32 v136, 0
	v_mov_b32_e32 v137, 0
	v_mov_b32_e32 v138, 0
	v_mov_b32_e32 v139, 0
	s_and_saveexec_b64 s[80:81], vcc
	s_cbranch_execz .Lvpf_join
	v_readlane_b32 vcc_lo, v255, 6
	v_readlane_b32 vcc_hi, v255, 7
	s_ashr_i32 s59, s33, 6
	v_add_u32_e32 v18, s58, v250
	v_lshl_add_u32 v18, s59, 11, v18
	s_and_b32 s58, s33, 3
	s_lshl_b32 s58, s58, 7
	s_mov_b32 s59, 0
	v_mov_b64_e32 v[16:17], vcc
	v_mad_i64_i32 v[16:17], vcc, v18, s65, v[16:17]
	v_lshl_add_u64 v[16:17], v[16:17], 0, s[58:59]
	v_lshl_add_u64 v[16:17], v[16:17], 0, v[248:249]
	s_movk_i32 s58, 0x6000
	global_load_dwordx4 v[122:125], v[16:17], off offset:2560
	v_lshl_add_u64 v[16:17], v[16:17], 0, s[58:59]
	global_load_dwordx4 v[128:131], v[16:17], off offset:2560
	v_lshl_add_u64 v[16:17], v[16:17], 0, s[58:59]
	global_load_dwordx4 v[132:135], v[16:17], off offset:2560
	v_lshl_add_u64 v[16:17], v[16:17], 0, s[58:59]
	global_load_dwordx4 v[136:139], v[16:17], off offset:2560
